# strategy 4: static s_setprio 1 for waves 4-7 during the attention steps (reset at phase exit)
# baseline (speedup 1.0000x reference)
; __device__ __forceinline__ void qk_prep_store(u32x4 a, u32x4 b, const float* gain, int sub, int pos, float scale, bf16_t* dst, int lane) {
;     ...
;     u32x4 o0, o1;
;     o0.x = pk2(x[0] * scale, x[1] * scale); o0.y = pk2(x[2] * scale, x[3] * scale); o0.z = pk2(x[4] * scale, x[5] * scale); o0.w = pk2(x[6] * scale, x[7] * scale);
;     o1.x = pk2(x[8] * scale, x[9] * scale); o1.y = pk2(x[10] * scale, x[11] * scale); o1.z = pk2(x[12] * scale, x[13] * scale); o1.w = pk2(x[14] * scale, x[15] * scale);
;     *(u32x4*)dst = o0; *(u32x4*)(dst + 8) = o1;
; __device__ __forceinline__ void ph_attn(KP p, int l, unsigned char* sm, int wv) {
;     ...
;             __syncthreads();
;             bf16x8 qf[2];
; #pragma unroll
;             for (int ks = 0; ks < 2; ++ks) qf[ks] = *(const bf16x8*)(Qs + (16 * wid + fr) * 72 + 32 * ks + 8 * fq);
;             f32x4 o[4];
; #pragma unroll
;             for (int dt = 0; dt < 4; ++dt) o[dt] = (f32x4){0.f, 0.f, 0.f, 0.f};
;             float mrun = p->sink[l * 8 + h] * 1.4426950408889634f;
;             float lsum = fq == 0 ? 1.0f : 0.0f;
;             const int qi = 16 * wid + fr;
;             for (int s = 0; s < 9; ++s) {
;                 const int kk0 = 16 * wid + 32 * s;
;                 f32x4 st[2];
; #pragma unroll
;                 for (int kt = 0; kt < 2; ++kt) {
;                     st[kt] = (f32x4){0.f, 0.f, 0.f, 0.f};
; #pragma unroll
;                     for (int ks = 0; ks < 2; ++ks) {
;                         const bf16x8 kf = *(const bf16x8*)(Ks + (kk0 + 16 * kt + fr) * 72 + 32 * ks + 8 * fq);
;                         st[kt] = __builtin_amdgcn_mfma_f32_16x16x32_bf16(kf, qf[ks], st[kt], 0, 0, 0);
;                     }
;                 }
;                 float sv[2][4]; float mx = -1e30f;
;                 if (interior && s >= 1 && s <= 7) {
; #pragma unroll
;                     for (int kt = 0; kt < 2; ++kt)
; #pragma unroll
;                         for (int r = 0; r < 4; ++r) { sv[kt][r] = st[kt][r]; mx = fmaxf(mx, sv[kt][r]); }
;                 } else {
; #pragma unroll
;                     for (int kt = 0; kt < 2; ++kt)
; #pragma unroll
;                         for (int r = 0; r < 4; ++r) {
;                             const int kk = kk0 + 16 * kt + 4 * fq + r, d = kk - 128 - qi, prel = Q0rel + kk - 128;
.LBB0_846:
	s_or_b64 exec, exec, s[2:3]
	v_mul_f32_e32 v41, 0x3e38aa3b, v50
	v_mul_f32_e32 v43, 0x3e38aa3b, v51
	v_cvt_pk_bf16_f32 v50, v41, v43
	v_mul_f32_e32 v41, 0x3e38aa3b, v48
	v_mul_f32_e32 v43, 0x3e38aa3b, v49
	v_cvt_pk_bf16_f32 v51, v41, v43
	v_mul_f32_e32 v41, 0x3e38aa3b, v46
	v_mul_f32_e32 v34, 0x3e38aa3b, v34
	v_mul_f32_e32 v35, 0x3e38aa3b, v35
	v_readlane_b32 s2, v254, 22
	v_mul_f32_e32 v43, 0x3e38aa3b, v47
	v_cvt_pk_bf16_f32 v52, v41, v43
	v_mul_f32_e32 v41, 0x3e38aa3b, v42
	v_mul_f32_e32 v42, 0x3e38aa3b, v45
	v_cvt_pk_bf16_f32 v53, v41, v42
	v_mul_f32_e32 v38, 0x3e38aa3b, v38
	v_mul_f32_e32 v39, 0x3e38aa3b, v39
	v_cvt_pk_bf16_f32 v46, v38, v39
	v_mul_f32_e32 v36, 0x3e38aa3b, v36
	v_mul_f32_e32 v37, 0x3e38aa3b, v37
	v_cvt_pk_bf16_f32 v47, v36, v37
	v_cvt_pk_bf16_f32 v48, v34, v35
	v_mul_f32_e32 v34, 0x3e38aa3b, v40
	v_mul_f32_e32 v35, 0x3e38aa3b, v44
	v_readlane_b32 s3, v254, 23
	v_cvt_pk_bf16_f32 v49, v34, v35
	ds_write_b128 v98, v[50:53]
	ds_write_b128 v98, v[46:49] offset:16
	s_waitcnt lgkmcnt(0)
	s_barrier
	v_readlane_b32 s98, v254, 4
	s_nop 0
	s_cmpk_lt_u32 s98, 0x100
	s_cbranch_scc1 .Lmy_attn_prio_done
	s_setprio 1
.Lmy_attn_prio_done:
	ds_read_b128 v[38:41], v156
	ds_read_b128 v[34:37], v156 offset:64
	s_load_dwordx2 s[2:3], s[2:3], 0x40
	s_add_i32 s40, s39, s38
	s_add_i32 s18, s40, s31
	s_ashr_i32 s19, s18, 31
	s_lshl_b64 s[18:19], s[18:19], 2
	s_waitcnt lgkmcnt(0)
	s_add_u32 s2, s2, s18
	s_addc_u32 s3, s3, s19
	global_load_dword v54, v1, s[2:3]
	v_add_u32_e32 v50, v102, v100
	ds_read_b128 v[42:45], v50
	ds_read_b128 v[46:49], v50 offset:64
	ds_read_b128 v[224:227], v50 offset:2304
	ds_read_b128 v[182:185], v50 offset:2368
	s_waitcnt lgkmcnt(3)
	v_mfma_f32_16x16x32_bf16 v[42:45], v[42:45], v[38:41], 0
	s_mov_b32 s2, 0x3fb8aa3b
	v_add_u32_e32 v159, 0xe000, v140
	s_mov_b32 s42, 0
	s_waitcnt lgkmcnt(2)
	v_mfma_f32_16x16x32_bf16 v[42:45], v[46:49], v[34:37], v[42:45]
	ds_read2_b64 v[186:189], v159 offset0:32 offset1:36
	ds_read2_b64 v[198:201], v150 offset1:4
	ds_read2_b64 v[190:193], v148 offset1:4
	ds_read2_b64 v[194:197], v149 offset1:4
	s_waitcnt vmcnt(0)
	v_mul_f32_e32 v55, 0x3fb8aa3b, v54
	s_waitcnt lgkmcnt(5)
	v_mfma_f32_16x16x32_bf16 v[46:49], v[224:227], v[38:41], 0
	s_nop 1
	v_cndmask_b32_e64 v42, v243, v42, s[88:89]
	v_cndmask_b32_e64 v43, v243, v43, s[90:91]
	v_cndmask_b32_e64 v44, v243, v44, s[92:93]
	s_waitcnt lgkmcnt(4)
	v_mfma_f32_16x16x32_bf16 v[46:49], v[182:185], v[34:37], v[46:49]
	v_max3_f32 v50, v42, s35, v43
	v_cndmask_b32_e64 v45, v243, v45, s[94:95]
	v_max3_f32 v50, v50, v44, v45
	s_nop 4
	v_cndmask_b32_e64 v46, v243, v46, s[96:97]
	v_cndmask_b32_e64 v47, v243, v47, s[16:17]
	v_max3_f32 v50, v50, v46, v47
	v_cndmask_b32_e64 v48, v243, v48, s[14:15]
	v_cndmask_b32_e64 v49, v243, v49, s[0:1]
	v_max3_f32 v50, v50, v48, v49
	v_mov_b32_e32 v51, v50
	s_nop 1
	v_permlane16_swap_b32_e32 v50, v51
	s_nop 0
	s_waitcnt lgkmcnt(0)
	v_max_f32_e32 v51, v51, v51
	v_max_f32_e32 v50, v50, v51
	v_mov_b32_e32 v51, v50
	s_nop 1
	v_permlane32_swap_b32_e32 v50, v51
	s_nop 0
	s_waitcnt lgkmcnt(0)
	v_max3_f32 v163, v55, v50, v51
	v_sub_f32_e32 v42, v42, v163
	v_exp_f32_e32 v59, v42
	v_sub_f32_e32 v42, v43, v163
	v_exp_f32_e32 v64, v42
	v_sub_f32_e32 v42, v44, v163
	v_exp_f32_e32 v65, v42
	v_sub_f32_e32 v42, v45, v163
	v_exp_f32_e32 v160, v42
	v_sub_f32_e32 v42, v46, v163
	v_exp_f32_e32 v161, v42
	v_sub_f32_e32 v42, v47, v163
	v_exp_f32_e32 v162, v42
	v_sub_f32_e32 v42, v48, v163
	v_fma_f32 v50, v54, s2, -v163
	v_exp_f32_e32 v168, v42
	v_sub_f32_e32 v42, v49, v163
	v_exp_f32_e32 v169, v42
	v_exp_f32_e32 v58, v50
	v_cvt_pk_bf16_f32 v54, v59, v64
	v_cvt_pk_bf16_f32 v55, v65, v160
	v_cvt_pk_bf16_f32 v56, v161, v162
	v_cvt_pk_bf16_f32 v57, v168, v169
	s_nop 0
	v_cmp_neq_f32_e32 vcc, 1.0, v58
	s_cmp_eq_u64 vcc, 0
	s_cselect_b64 s[2:3], -1, 0
	v_mul_f32_e32 v46, 0, v58
	v_cndmask_b32_e64 v60, v46, 0, s[2:3]
	v_mov_b32_e32 v61, v60
	v_mov_b32_e32 v62, v60
	v_mov_b32_e32 v63, v60
	s_nop 0
	s_waitcnt lgkmcnt(0)
	v_mfma_f32_16x16x32_bf16 v[46:49], v[186:189], v[54:57], v[60:63]
	s_nop 0
	s_waitcnt lgkmcnt(0)
	v_mfma_f32_16x16x32_bf16 v[50:53], v[190:193], v[54:57], v[60:63]
	s_nop 0
	s_waitcnt lgkmcnt(0)
	v_mfma_f32_16x16x32_bf16 v[42:45], v[194:197], v[54:57], v[60:63]
	s_nop 2
	v_mul_f32_e64 v60, v58, 0
	v_mul_f32_e64 v61, v58, 0
	v_add_f32_e32 v59, 0, v59
	v_add_f32_e32 v59, v64, v59
	v_add_f32_e32 v59, v65, v59
	v_cndmask_b32_e64 v61, v61, 0, s[2:3]
	v_cndmask_b32_e64 v60, v60, 0, s[2:3]
	v_add_f32_e32 v59, v160, v59
	v_mov_b32_e32 v62, v60
	v_mov_b32_e32 v63, v61
	v_add_f32_e32 v59, v161, v59
	v_add_f32_e32 v59, v162, v59
	v_mfma_f32_16x16x32_bf16 v[54:57], v[198:201], v[54:57], v[60:63]
	v_add_f32_e32 v59, v168, v59
	v_add_f32_e32 v162, v169, v59
	v_fmac_f32_e32 v162, v101, v58
	v_mov_b32_e32 v160, v152
	v_mov_b32_e32 v161, v151
	ds_read_b128 v[186:189], v160
	ds_read_b128 v[190:193], v160 offset:64
	ds_read_b128 v[194:197], v160 offset:2304
	ds_read_b128 v[198:201], v160 offset:2368

; __device__ __forceinline__ void ph_attn(KP p, int l, unsigned char* sm, int wv) {
;     ...
;         }
;     }
; }
.LBB0_853:
	s_setprio 0
	s_mov_b64 s[0:1], 0
	s_movk_i32 s60, 0x800
	s_movk_i32 s61, 0x1000
	s_movk_i32 s62, 0x3000
	s_movk_i32 s63, 0x600
	s_movk_i32 s66, 0x404
	s_mov_b64 s[68:69], 0x800
